# GEMM K-loop: snake order of the 8 MFMAs per k-group so only one operand changes between consecutive MFMAs (bit-identical)
# baseline (speedup 1.0000x reference)
; #define PG8_STAGE(bufoff, gbase, voff) do { _Pragma("unroll") for (int _i = 0; _i < 2; ++_i) \
;         __builtin_amdgcn_global_load_lds((const unsigned*)((const char*)(gbase) + (voff)[_i]), (PG8_LAS unsigned*)(lds + (bufoff) + ldsw + _i * 8192), 16, 0, 0); } while (0)
; #define PG8_LDA(dst, b, h) do { _Pragma("unroll") for (int m = 0; m < 4; ++m) _Pragma("unroll") for (int k = 0; k < 2; ++k) dst[m][k] = *(const PG8_LAS bf16x8*)(lds + PG8_SA(b, h) + aoff + m * 2048 + k * 1024); } while (0)
; #define PG8_LDB(dst, b, h) do { _Pragma("unroll") for (int n = 0; n < 2; ++n) _Pragma("unroll") for (int k = 0; k < 2; ++k) dst[n][k] = *(const PG8_LAS bf16x8*)(lds + PG8_SB(b, h) + boff + n * 2048 + k * 1024); } while (0)
; #define PG8_MMA(ai, bj, At, Bt) do { __builtin_amdgcn_s_setprio(1); _Pragma("unroll") for (int m = 0; m < 4; ++m) _Pragma("unroll") for (int n = 0; n < 2; ++n) _Pragma("unroll") for (int k = 0; k < 2; ++k) \
;         acc[ai][bj][m][n] = __builtin_amdgcn_mfma_f32_16x16x32_bf16(Bt[n][k], At[m][k], acc[ai][bj][m][n], 0, 0, 0); __builtin_amdgcn_s_setprio(0); } while (0)
; #define PG8_WAIT_V(n) asm volatile("s_waitcnt vmcnt(" #n ")" ::: "memory")
; #define PG8_WAIT_L(n) asm volatile("s_waitcnt lgkmcnt(" #n ")" ::: "memory")
; #define PG8_BAR __builtin_amdgcn_s_barrier()
; #define PG8_SCHED __builtin_amdgcn_sched_barrier(0)
; template <class Epi, class Sched, bool ALIGN_EPI = false, bool SP2 = false>
; __device__ __forceinline__ void gemm_phase(PG8_LAS unsigned char* lds, const Gemm g, const Sched& S, const Epi& E) {
;     ...
;             PG8_LDB(B0, 0, 0); PG8_LDB(B1, 0, 1); PG8_SCHED; PG8_LDA(At, 0, 0); PG8_STAGE(PG8_SA(1, 1), a1 + hstep, voffA);
;             PG8_WAIT_V(8); PG8_WAIT_L(0); PG8_BAR; PG8_MMA(0, 0, At, B0); PG8_MMA(0, 1, At, B1); PG8_BAR; PG8_SCHED;
;             PG8_LDA(At, 0, 1); PG8_STAGE(PG8_SB(0, 0), b2, voffB); PG8_STAGE(PG8_SB(0, 1), b2 + hstep, voffB); PG8_STAGE(PG8_SA(0, 0), a2, voffA);
;             PG8_WAIT_V(8); PG8_WAIT_L(0); PG8_BAR; PG8_MMA(1, 0, At, B0); PG8_MMA(1, 1, At, B1); PG8_BAR; PG8_SCHED;
.LBB0_322:
	s_add_i32 s42, s14, 2
	s_add_u32 s43, s12, 0x80
	s_addc_u32 s15, s13, 0
	s_add_i32 s75, 0, 0x10000
	s_cmp_eq_u32 s25, s14
	s_cselect_b32 s15, s55, s15
	s_cselect_b32 s14, s54, s43
	s_cselect_b32 vcc_hi, s65, s17
	s_cselect_b32 vcc_lo, s64, s16
	s_add_i32 s43, 0, 0x14000
	v_add_u32_e32 v142, s75, v199
	v_add_u32_e32 v178, s43, v199
	ds_read_b128 v[130:133], v142
	ds_read_b128 v[134:137], v142 offset:1024
	ds_read_b128 v[138:141], v142 offset:2048
	ds_read_b128 v[142:145], v142 offset:3072
	ds_read_b128 v[170:173], v178
	ds_read_b128 v[174:177], v178 offset:1024
	ds_read_b128 v[202:205], v178 offset:2048
	ds_read_b128 v[206:209], v178 offset:3072
	v_lshl_add_u64 v[178:179], s[12:13], 0, v[166:167]
	s_add_i32 m0, s56, 0xc000
	ds_read_b128 v[210:213], v201
	ds_read_b128 v[214:217], v201 offset:1024
	ds_read_b128 v[218:221], v201 offset:2048
	ds_read_b128 v[222:225], v201 offset:3072
	ds_read_b128 v[226:229], v201 offset:4096
	ds_read_b128 v[230:233], v201 offset:5120
	ds_read_b128 v[234:237], v201 offset:6144
	ds_read_b128 v[238:241], v201 offset:7168
	global_load_lds_dwordx4 v[178:179], off
	v_lshl_add_u64 v[178:179], s[12:13], 0, v[168:169]
	s_add_i32 m0, s56, 0xe000
	s_nop 0
	global_load_lds_dwordx4 v[178:179], off
	s_waitcnt vmcnt(8)
	s_waitcnt lgkmcnt(0)
	s_barrier
	s_setprio 1
	s_waitcnt lgkmcnt(0)
	v_mfma_f32_16x16x32_bf16 v[126:129], v[130:133], v[210:213], v[126:129]
	v_mfma_f32_16x16x32_bf16 v[122:125], v[138:141], v[210:213], v[122:125]
	v_mfma_f32_16x16x32_bf16 v[106:109], v[138:141], v[218:221], v[106:109]
	v_mfma_f32_16x16x32_bf16 v[110:113], v[130:133], v[218:221], v[110:113]
	v_mfma_f32_16x16x32_bf16 v[94:97], v[130:133], v[226:229], v[94:97]
	v_mfma_f32_16x16x32_bf16 v[90:93], v[138:141], v[226:229], v[90:93]
	v_mfma_f32_16x16x32_bf16 v[74:77], v[138:141], v[234:237], v[74:77]
	v_mfma_f32_16x16x32_bf16 v[78:81], v[130:133], v[234:237], v[78:81]
	v_mfma_f32_16x16x32_bf16 v[126:129], v[134:137], v[214:217], v[126:129]
	v_mfma_f32_16x16x32_bf16 v[122:125], v[142:145], v[214:217], v[122:125]
	v_mfma_f32_16x16x32_bf16 v[106:109], v[142:145], v[222:225], v[106:109]
	v_mfma_f32_16x16x32_bf16 v[110:113], v[134:137], v[222:225], v[110:113]
	v_mfma_f32_16x16x32_bf16 v[94:97], v[134:137], v[230:233], v[94:97]
	v_mfma_f32_16x16x32_bf16 v[90:93], v[142:145], v[230:233], v[90:93]
	v_mfma_f32_16x16x32_bf16 v[74:77], v[142:145], v[238:241], v[74:77]
	v_mfma_f32_16x16x32_bf16 v[78:81], v[134:137], v[238:241], v[78:81]
	s_setprio 0
	s_setprio 1
	v_mfma_f32_16x16x32_bf16 v[118:121], v[170:173], v[210:213], v[118:121]
	v_mfma_f32_16x16x32_bf16 v[114:117], v[202:205], v[210:213], v[114:117]
	v_mfma_f32_16x16x32_bf16 v[98:101], v[202:205], v[218:221], v[98:101]
	v_mfma_f32_16x16x32_bf16 v[102:105], v[170:173], v[218:221], v[102:105]
	v_mfma_f32_16x16x32_bf16 v[86:89], v[170:173], v[226:229], v[86:89]
	v_mfma_f32_16x16x32_bf16 v[82:85], v[202:205], v[226:229], v[82:85]
	v_mfma_f32_16x16x32_bf16 v[66:69], v[202:205], v[234:237], v[66:69]
	v_mfma_f32_16x16x32_bf16 v[70:73], v[170:173], v[234:237], v[70:73]
	v_mfma_f32_16x16x32_bf16 v[118:121], v[174:177], v[214:217], v[118:121]
	v_mfma_f32_16x16x32_bf16 v[114:117], v[206:209], v[214:217], v[114:117]
	v_mfma_f32_16x16x32_bf16 v[98:101], v[206:209], v[222:225], v[98:101]
	v_mfma_f32_16x16x32_bf16 v[102:105], v[174:177], v[222:225], v[102:105]
	v_mfma_f32_16x16x32_bf16 v[86:89], v[174:177], v[230:233], v[86:89]
	v_mfma_f32_16x16x32_bf16 v[82:85], v[206:209], v[230:233], v[82:85]
	v_mfma_f32_16x16x32_bf16 v[66:69], v[206:209], v[238:241], v[66:69]
	v_mfma_f32_16x16x32_bf16 v[70:73], v[174:177], v[238:241], v[70:73]
	s_setprio 0
	s_barrier
	s_add_i32 s75, s75, s23
	v_lshl_add_u64 v[178:179], vcc, 0, v[0:1]
	s_mov_b32 m0, s75
	ds_read_b128 v[210:213], v201 offset:16384
	ds_read_b128 v[214:217], v201 offset:17408
	ds_read_b128 v[218:221], v201 offset:18432
	ds_read_b128 v[222:225], v201 offset:19456
	ds_read_b128 v[226:229], v201 offset:20480
	ds_read_b128 v[230:233], v201 offset:21504
	ds_read_b128 v[234:237], v201 offset:22528
	ds_read_b128 v[238:241], v201 offset:23552
	global_load_lds_dwordx4 v[178:179], off
	s_add_i32 m0, s75, 0x2000
	v_lshl_add_u64 v[242:243], vcc, 0, v[162:163]
	s_add_u32 vcc_lo, vcc_lo, s84
	s_addc_u32 vcc_hi, vcc_hi, 0
	s_add_i32 s43, s43, s23
	global_load_lds_dwordx4 v[242:243], off
	v_lshl_add_u64 v[244:245], vcc, 0, v[0:1]
	s_mov_b32 m0, s43
	v_lshl_add_u64 v[246:247], vcc, 0, v[162:163]
	global_load_lds_dwordx4 v[244:245], off
	s_add_i32 m0, s43, 0x2000
	v_lshl_add_u64 v[248:249], s[14:15], 0, v[158:159]
	global_load_lds_dwordx4 v[246:247], off
	s_mov_b32 m0, s56
	v_lshl_add_u64 v[250:251], s[14:15], 0, v[160:161]
	global_load_lds_dwordx4 v[248:249], off
	s_mov_b32 m0, s82
	s_nop 0
	global_load_lds_dwordx4 v[250:251], off
	s_waitcnt vmcnt(8)
	s_waitcnt lgkmcnt(0)
	s_barrier
; #define PG8_STAGE(bufoff, gbase, voff) do { _Pragma("unroll") for (int _i = 0; _i < 2; ++_i) \
;         __builtin_amdgcn_global_load_lds((const unsigned*)((const char*)(gbase) + (voff)[_i]), (PG8_LAS unsigned*)(lds + (bufoff) + ldsw + _i * 8192), 16, 0, 0); } while (0)
; #define PG8_LDA(dst, b, h) do { _Pragma("unroll") for (int m = 0; m < 4; ++m) _Pragma("unroll") for (int k = 0; k < 2; ++k) dst[m][k] = *(const PG8_LAS bf16x8*)(lds + PG8_SA(b, h) + aoff + m * 2048 + k * 1024); } while (0)
; #define PG8_LDB(dst, b, h) do { _Pragma("unroll") for (int n = 0; n < 2; ++n) _Pragma("unroll") for (int k = 0; k < 2; ++k) dst[n][k] = *(const PG8_LAS bf16x8*)(lds + PG8_SB(b, h) + boff + n * 2048 + k * 1024); } while (0)
; #define PG8_MMA(ai, bj, At, Bt) do { __builtin_amdgcn_s_setprio(1); _Pragma("unroll") for (int m = 0; m < 4; ++m) _Pragma("unroll") for (int n = 0; n < 2; ++n) _Pragma("unroll") for (int k = 0; k < 2; ++k) \
;         acc[ai][bj][m][n] = __builtin_amdgcn_mfma_f32_16x16x32_bf16(Bt[n][k], At[m][k], acc[ai][bj][m][n], 0, 0, 0); __builtin_amdgcn_s_setprio(0); } while (0)
; #define PG8_WAIT_V(n) asm volatile("s_waitcnt vmcnt(" #n ")" ::: "memory")
; #define PG8_WAIT_L(n) asm volatile("s_waitcnt lgkmcnt(" #n ")" ::: "memory")
; #define PG8_BAR __builtin_amdgcn_s_barrier()
; #define PG8_SCHED __builtin_amdgcn_sched_barrier(0)
; template <class Epi, class Sched, bool ALIGN_EPI = false, bool SP2 = false>
; __device__ __forceinline__ void gemm_phase(PG8_LAS unsigned char* lds, const Gemm g, const Sched& S, const Epi& E) {
;     ...
;             PG8_WAIT_V(8); PG8_WAIT_L(0); PG8_BAR; PG8_MMA(1, 0, At, B0); PG8_MMA(1, 1, At, B1); PG8_BAR; PG8_SCHED;
;             PG8_LDB(B0, 1, 0); PG8_LDB(B1, 1, 1); PG8_SCHED; PG8_LDA(At, 1, 0); PG8_STAGE(PG8_SA(0, 1), a2 + hstep, voffA);
;             PG8_WAIT_V(8); PG8_WAIT_L(0); PG8_BAR; PG8_MMA(0, 0, At, B0); PG8_MMA(0, 1, At, B1); PG8_BAR; PG8_SCHED;
	s_setprio 1
	s_waitcnt lgkmcnt(0)
	v_mfma_f32_16x16x32_bf16 v[62:65], v[130:133], v[210:213], v[62:65]
	v_mfma_f32_16x16x32_bf16 v[58:61], v[138:141], v[210:213], v[58:61]
	v_mfma_f32_16x16x32_bf16 v[42:45], v[138:141], v[218:221], v[42:45]
	v_mfma_f32_16x16x32_bf16 v[46:49], v[130:133], v[218:221], v[46:49]
	v_mfma_f32_16x16x32_bf16 v[30:33], v[130:133], v[226:229], v[30:33]
	v_mfma_f32_16x16x32_bf16 v[26:29], v[138:141], v[226:229], v[26:29]
	v_mfma_f32_16x16x32_bf16 v[10:13], v[138:141], v[234:237], v[10:13]
	v_mfma_f32_16x16x32_bf16 v[14:17], v[130:133], v[234:237], v[14:17]
	v_mfma_f32_16x16x32_bf16 v[62:65], v[134:137], v[214:217], v[62:65]
	v_mfma_f32_16x16x32_bf16 v[58:61], v[142:145], v[214:217], v[58:61]
	v_mfma_f32_16x16x32_bf16 v[42:45], v[142:145], v[222:225], v[42:45]
	v_mfma_f32_16x16x32_bf16 v[46:49], v[134:137], v[222:225], v[46:49]
	v_mfma_f32_16x16x32_bf16 v[30:33], v[134:137], v[230:233], v[30:33]
	v_mfma_f32_16x16x32_bf16 v[26:29], v[142:145], v[230:233], v[26:29]
	v_mfma_f32_16x16x32_bf16 v[10:13], v[142:145], v[238:241], v[10:13]
	v_mfma_f32_16x16x32_bf16 v[14:17], v[134:137], v[238:241], v[14:17]
	s_setprio 0
	s_setprio 1
	v_mfma_f32_16x16x32_bf16 v[54:57], v[170:173], v[210:213], v[54:57]
	v_mfma_f32_16x16x32_bf16 v[50:53], v[202:205], v[210:213], v[50:53]
	v_mfma_f32_16x16x32_bf16 v[34:37], v[202:205], v[218:221], v[34:37]
	v_mfma_f32_16x16x32_bf16 v[38:41], v[170:173], v[218:221], v[38:41]
	v_mfma_f32_16x16x32_bf16 v[22:25], v[170:173], v[226:229], v[22:25]
	v_mfma_f32_16x16x32_bf16 v[18:21], v[202:205], v[226:229], v[18:21]
	v_mfma_f32_16x16x32_bf16 v[2:5], v[202:205], v[234:237], v[2:5]
	v_mfma_f32_16x16x32_bf16 v[6:9], v[170:173], v[234:237], v[6:9]
	v_mfma_f32_16x16x32_bf16 v[54:57], v[174:177], v[214:217], v[54:57]
	v_mfma_f32_16x16x32_bf16 v[50:53], v[206:209], v[214:217], v[50:53]
	v_mfma_f32_16x16x32_bf16 v[34:37], v[206:209], v[222:225], v[34:37]
	v_mfma_f32_16x16x32_bf16 v[38:41], v[174:177], v[222:225], v[38:41]
	v_mfma_f32_16x16x32_bf16 v[22:25], v[174:177], v[230:233], v[22:25]
	v_mfma_f32_16x16x32_bf16 v[18:21], v[206:209], v[230:233], v[18:21]
	v_mfma_f32_16x16x32_bf16 v[2:5], v[206:209], v[238:241], v[2:5]
	v_mfma_f32_16x16x32_bf16 v[6:9], v[174:177], v[238:241], v[6:9]
	s_setprio 0
	s_barrier
	s_add_i32 s43, 0, 0x18000
	s_add_i32 s75, 0, 0x1c000
	v_add_u32_e32 v142, s43, v199
	v_add_u32_e32 v206, s75, v199
	ds_read_b128 v[130:133], v142
	ds_read_b128 v[134:137], v142 offset:1024
	ds_read_b128 v[138:141], v142 offset:2048
	ds_read_b128 v[142:145], v142 offset:3072
	ds_read_b128 v[170:173], v206
	ds_read_b128 v[174:177], v206 offset:1024
	ds_read_b128 v[202:205], v206 offset:2048
	ds_read_b128 v[206:209], v206 offset:3072
	s_add_u32 s14, s14, s84
	s_addc_u32 s15, s15, 0
	s_mov_b32 m0, s83
	v_lshl_add_u64 v[252:253], s[14:15], 0, v[158:159]
	ds_read_b128 v[210:213], v201 offset:32768
	ds_read_b128 v[214:217], v201 offset:33792
	ds_read_b128 v[218:221], v201 offset:34816
	ds_read_b128 v[222:225], v201 offset:35840
	ds_read_b128 v[226:229], v201 offset:36864
	ds_read_b128 v[230:233], v201 offset:37888
	ds_read_b128 v[234:237], v201 offset:38912
	ds_read_b128 v[238:241], v201 offset:39936
	global_load_lds_dwordx4 v[252:253], off
	v_lshl_add_u64 v[252:253], s[14:15], 0, v[160:161]
	s_mov_b32 m0, s24
	s_nop 0
	global_load_lds_dwordx4 v[252:253], off
	s_waitcnt vmcnt(8)
	s_waitcnt lgkmcnt(0)
	s_barrier
	s_setprio 1
	s_waitcnt lgkmcnt(0)
	v_mfma_f32_16x16x32_bf16 v[126:129], v[130:133], v[210:213], v[126:129]
	v_mfma_f32_16x16x32_bf16 v[122:125], v[138:141], v[210:213], v[122:125]
	v_mfma_f32_16x16x32_bf16 v[106:109], v[138:141], v[218:221], v[106:109]
	v_mfma_f32_16x16x32_bf16 v[110:113], v[130:133], v[218:221], v[110:113]
	v_mfma_f32_16x16x32_bf16 v[94:97], v[130:133], v[226:229], v[94:97]
	v_mfma_f32_16x16x32_bf16 v[90:93], v[138:141], v[226:229], v[90:93]
	v_mfma_f32_16x16x32_bf16 v[74:77], v[138:141], v[234:237], v[74:77]
	v_mfma_f32_16x16x32_bf16 v[78:81], v[130:133], v[234:237], v[78:81]
	v_mfma_f32_16x16x32_bf16 v[126:129], v[134:137], v[214:217], v[126:129]
	v_mfma_f32_16x16x32_bf16 v[122:125], v[142:145], v[214:217], v[122:125]
	v_mfma_f32_16x16x32_bf16 v[106:109], v[142:145], v[222:225], v[106:109]
	v_mfma_f32_16x16x32_bf16 v[110:113], v[134:137], v[222:225], v[110:113]
	v_mfma_f32_16x16x32_bf16 v[94:97], v[134:137], v[230:233], v[94:97]
	v_mfma_f32_16x16x32_bf16 v[90:93], v[142:145], v[230:233], v[90:93]
	v_mfma_f32_16x16x32_bf16 v[74:77], v[142:145], v[238:241], v[74:77]
	v_mfma_f32_16x16x32_bf16 v[78:81], v[134:137], v[238:241], v[78:81]
	s_setprio 0
	s_setprio 1
	v_mfma_f32_16x16x32_bf16 v[118:121], v[170:173], v[210:213], v[118:121]
	v_mfma_f32_16x16x32_bf16 v[114:117], v[202:205], v[210:213], v[114:117]
	v_mfma_f32_16x16x32_bf16 v[98:101], v[202:205], v[218:221], v[98:101]
	v_mfma_f32_16x16x32_bf16 v[102:105], v[170:173], v[218:221], v[102:105]
	v_mfma_f32_16x16x32_bf16 v[86:89], v[170:173], v[226:229], v[86:89]
	v_mfma_f32_16x16x32_bf16 v[82:85], v[202:205], v[226:229], v[82:85]
	v_mfma_f32_16x16x32_bf16 v[66:69], v[202:205], v[234:237], v[66:69]
	v_mfma_f32_16x16x32_bf16 v[70:73], v[170:173], v[234:237], v[70:73]
	v_mfma_f32_16x16x32_bf16 v[118:121], v[174:177], v[214:217], v[118:121]
	v_mfma_f32_16x16x32_bf16 v[114:117], v[206:209], v[214:217], v[114:117]
	v_mfma_f32_16x16x32_bf16 v[98:101], v[206:209], v[222:225], v[98:101]
	v_mfma_f32_16x16x32_bf16 v[102:105], v[174:177], v[222:225], v[102:105]
	v_mfma_f32_16x16x32_bf16 v[86:89], v[174:177], v[230:233], v[86:89]
	v_mfma_f32_16x16x32_bf16 v[82:85], v[206:209], v[230:233], v[82:85]
	v_mfma_f32_16x16x32_bf16 v[66:69], v[206:209], v[238:241], v[66:69]
	v_mfma_f32_16x16x32_bf16 v[70:73], v[174:177], v[238:241], v[70:73]
	s_setprio 0
	s_barrier
; #define PG8_STAGE(bufoff, gbase, voff) do { _Pragma("unroll") for (int _i = 0; _i < 2; ++_i) \
;         __builtin_amdgcn_global_load_lds((const unsigned*)((const char*)(gbase) + (voff)[_i]), (PG8_LAS unsigned*)(lds + (bufoff) + ldsw + _i * 8192), 16, 0, 0); } while (0)
; #define PG8_LDA(dst, b, h) do { _Pragma("unroll") for (int m = 0; m < 4; ++m) _Pragma("unroll") for (int k = 0; k < 2; ++k) dst[m][k] = *(const PG8_LAS bf16x8*)(lds + PG8_SA(b, h) + aoff + m * 2048 + k * 1024); } while (0)
; #define PG8_MMA(ai, bj, At, Bt) do { __builtin_amdgcn_s_setprio(1); _Pragma("unroll") for (int m = 0; m < 4; ++m) _Pragma("unroll") for (int n = 0; n < 2; ++n) _Pragma("unroll") for (int k = 0; k < 2; ++k) \
;         acc[ai][bj][m][n] = __builtin_amdgcn_mfma_f32_16x16x32_bf16(Bt[n][k], At[m][k], acc[ai][bj][m][n], 0, 0, 0); __builtin_amdgcn_s_setprio(0); } while (0)
; #define PG8_WAIT_V(n) asm volatile("s_waitcnt vmcnt(" #n ")" ::: "memory")
; #define PG8_WAIT_L(n) asm volatile("s_waitcnt lgkmcnt(" #n ")" ::: "memory")
; #define PG8_BAR __builtin_amdgcn_s_barrier()
; #define PG8_SCHED __builtin_amdgcn_sched_barrier(0)
; template <class Epi, class Sched, bool ALIGN_EPI = false, bool SP2 = false>
; __device__ __forceinline__ void gemm_phase(PG8_LAS unsigned char* lds, const Gemm g, const Sched& S, const Epi& E) {
;     ...
;         for (int t = 0; t < nt; t += 2) {
;     ...
;             PG8_LDA(At, 1, 1); PG8_STAGE(PG8_SB(1, 0), b3, voffB); PG8_STAGE(PG8_SB(1, 1), b3 + hstep, voffB); PG8_STAGE(PG8_SA(1, 0), a3, voffA);
;             PG8_WAIT_V(8); PG8_WAIT_L(0); PG8_BAR; PG8_MMA(1, 0, At, B0); PG8_MMA(1, 1, At, B1); PG8_BAR; PG8_SCHED;
	s_add_i32 s14, s43, s23
	v_lshl_add_u64 v[178:179], v[178:179], 0, s[94:95]
	s_mov_b32 m0, s14
	ds_read_b128 v[210:213], v201 offset:49152
	ds_read_b128 v[214:217], v201 offset:50176
	ds_read_b128 v[218:221], v201 offset:51200
	ds_read_b128 v[222:225], v201 offset:52224
	ds_read_b128 v[226:229], v201 offset:53248
	ds_read_b128 v[230:233], v201 offset:54272
	ds_read_b128 v[234:237], v201 offset:55296
	ds_read_b128 v[238:241], v201 offset:56320
	global_load_lds_dwordx4 v[178:179], off
	v_lshl_add_u64 v[178:179], v[242:243], 0, s[94:95]
	s_add_i32 m0, s14, 0x2000
	s_add_i32 s14, s75, s23
	global_load_lds_dwordx4 v[178:179], off
	v_lshl_add_u64 v[178:179], v[244:245], 0, s[94:95]
	s_mov_b32 m0, s14
	s_nop 0
	global_load_lds_dwordx4 v[178:179], off
	v_lshl_add_u64 v[178:179], v[246:247], 0, s[94:95]
	s_add_i32 m0, s14, 0x2000
	s_nop 0
	global_load_lds_dwordx4 v[178:179], off
	v_lshl_add_u64 v[178:179], v[248:249], 0, s[94:95]
	s_mov_b32 m0, s63
	s_nop 0
	global_load_lds_dwordx4 v[178:179], off
	v_lshl_add_u64 v[178:179], v[250:251], 0, s[94:95]
	s_mov_b32 m0, s70
	s_nop 0
	global_load_lds_dwordx4 v[178:179], off
	s_waitcnt vmcnt(8)
	s_waitcnt lgkmcnt(0)
	s_barrier
	s_setprio 1
	s_waitcnt lgkmcnt(0)
	v_mfma_f32_16x16x32_bf16 v[62:65], v[130:133], v[210:213], v[62:65]
	v_mfma_f32_16x16x32_bf16 v[58:61], v[138:141], v[210:213], v[58:61]
	v_mfma_f32_16x16x32_bf16 v[42:45], v[138:141], v[218:221], v[42:45]
	v_mfma_f32_16x16x32_bf16 v[46:49], v[130:133], v[218:221], v[46:49]
	v_mfma_f32_16x16x32_bf16 v[30:33], v[130:133], v[226:229], v[30:33]
	v_mfma_f32_16x16x32_bf16 v[26:29], v[138:141], v[226:229], v[26:29]
	v_mfma_f32_16x16x32_bf16 v[10:13], v[138:141], v[234:237], v[10:13]
	v_mfma_f32_16x16x32_bf16 v[14:17], v[130:133], v[234:237], v[14:17]
	v_mfma_f32_16x16x32_bf16 v[62:65], v[134:137], v[214:217], v[62:65]
	v_mfma_f32_16x16x32_bf16 v[58:61], v[142:145], v[214:217], v[58:61]
	v_mfma_f32_16x16x32_bf16 v[42:45], v[142:145], v[222:225], v[42:45]
	v_mfma_f32_16x16x32_bf16 v[46:49], v[134:137], v[222:225], v[46:49]
	v_mfma_f32_16x16x32_bf16 v[30:33], v[134:137], v[230:233], v[30:33]
	v_mfma_f32_16x16x32_bf16 v[26:29], v[142:145], v[230:233], v[26:29]
	v_mfma_f32_16x16x32_bf16 v[10:13], v[142:145], v[238:241], v[10:13]
	v_mfma_f32_16x16x32_bf16 v[14:17], v[134:137], v[238:241], v[14:17]
	s_setprio 0
	s_setprio 1
	v_mfma_f32_16x16x32_bf16 v[54:57], v[170:173], v[210:213], v[54:57]
	v_mfma_f32_16x16x32_bf16 v[50:53], v[202:205], v[210:213], v[50:53]
	v_mfma_f32_16x16x32_bf16 v[34:37], v[202:205], v[218:221], v[34:37]
	v_mfma_f32_16x16x32_bf16 v[38:41], v[170:173], v[218:221], v[38:41]
	v_mfma_f32_16x16x32_bf16 v[22:25], v[170:173], v[226:229], v[22:25]
	v_mfma_f32_16x16x32_bf16 v[18:21], v[202:205], v[226:229], v[18:21]
	v_mfma_f32_16x16x32_bf16 v[2:5], v[202:205], v[234:237], v[2:5]
	v_mfma_f32_16x16x32_bf16 v[6:9], v[170:173], v[234:237], v[6:9]
	v_mfma_f32_16x16x32_bf16 v[54:57], v[174:177], v[214:217], v[54:57]
	v_mfma_f32_16x16x32_bf16 v[50:53], v[206:209], v[214:217], v[50:53]
	v_mfma_f32_16x16x32_bf16 v[34:37], v[206:209], v[222:225], v[34:37]
	v_mfma_f32_16x16x32_bf16 v[38:41], v[174:177], v[222:225], v[38:41]
	v_mfma_f32_16x16x32_bf16 v[22:25], v[174:177], v[230:233], v[22:25]
	v_mfma_f32_16x16x32_bf16 v[18:21], v[206:209], v[230:233], v[18:21]
	v_mfma_f32_16x16x32_bf16 v[2:5], v[206:209], v[238:241], v[2:5]
	v_mfma_f32_16x16x32_bf16 v[6:9], v[174:177], v[238:241], v[6:9]
	s_setprio 0
	s_barrier
	s_add_u32 s12, s12, 0x100
	s_addc_u32 s13, s13, 0
	s_add_u32 s16, s16, 0x100
	s_addc_u32 s17, s17, 0
	s_cmp_ge_u32 s42, s28
	s_mov_b32 s14, s42
	s_cbranch_scc0 .LBB0_322
	s_and_b64 vcc, exec, s[48:49]
	s_cbranch_vccnz .LBB0_326
	v_lshl_add_u32 v170, s72, 8, v157
	s_cmp_lt_i32 s57, 1
	s_mov_b64 s[12:13], -1
	s_cbranch_scc0 .LBB0_327
